# hand-written fill loops with a partial split: XQF_N 16128, L1FILL_NA 18432 (18 items per idle wave at each site)
# speedup vs baseline: 1.0018x; 1.0018x over previous
.LBB0_16:
	v_writelane_b32 v251, s95, 48
	s_andn2_b64 vcc, exec, s[0:1]
	v_writelane_b32 v251, s97, 49
	s_cbranch_vccnz .LBB0_538
	v_readlane_b32 s2, v251, 2
	v_readlane_b32 s3, v251, 3
	v_mov_b32 v1, 0
	s_and_b32 s85, s54, 0xffffffc0
	v_mbcnt_lo_u32_b32 v1, -1, v1
	v_mbcnt_hi_u32_b32 v2, -1, v1
	s_lshl_b32 s27, s95, 3
	s_lshl_b32 s4, s97, 3
	v_add_u32_e32 v3, s85, v2
	s_cmpk_eq_i32 s97, 0x100
	v_readfirstlane_b32 s29, v3
	s_cselect_b32 s11, 0x3f00, 0
	s_ashr_i32 s28, s29, 6
	s_mul_i32 s0, s28, 0x2100
	s_sub_i32 s5, 0x5600, s11
	s_lshl_b32 s96, s97, 9
	v_and_b32_e32 v1, 63, v2
	s_add_i32 s10, s0, 0
	s_add_i32 s26, s28, s27
	s_movk_i32 s13, 0x5600
	s_cmp_ge_i32 s26, s5
	v_lshrrev_b32_e32 v77, 4, v1
	v_lshlrev_b32_e32 v78, 2, v1
	v_and_b32_e32 v76, 7, v2
	v_lshrrev_b32_e32 v88, 3, v1
	s_mov_b32 s12, s26
	s_cbranch_scc1 .LBB0_84
	v_readlane_b32 s36, v251, 16
	v_mov_b32_e32 v2, 0
	v_readlane_b32 s44, v251, 24
	v_readlane_b32 s45, v251, 25
	v_lshlrev_b32_e32 v4, 4, v76
	v_mov_b32_e32 v5, v2
	s_cmp_lg_u64 s[44:45], 0
	v_lshl_add_u64 v[4:5], s[2:3], 0, v[4:5]
	s_mov_b64 s[0:1], 0x8c00000
	s_cselect_b64 s[6:7], -1, 0
	v_and_b32_e32 v79, 60, v78
	v_lshrrev_b32_e32 v81, 3, v1
	v_lshl_add_u64 v[70:71], v[4:5], 0, s[0:1]
	s_add_i32 s0, s11, s28
	v_lshl_add_u32 v3, v79, 2, s10
	v_mul_u32_u24_e32 v6, 0x104, v77
	v_mul_u32_u24_e32 v7, 0x410, v76
	v_lshlrev_b32_e32 v4, 2, v81
	s_add_i32 s0, s0, s27
	v_lshlrev_b32_e32 v80, 1, v77
	v_add3_u32 v82, s10, v7, v4
	v_or_b32_e32 v83, 8, v81
	v_or_b32_e32 v84, 16, v81
	v_or_b32_e32 v85, 24, v81
	v_or_b32_e32 v86, 32, v81
	v_or_b32_e32 v87, 40, v81
	v_or_b32_e32 v89, 48, v81
	v_or_b32_e32 v90, 56, v81
	s_lshl_b32 s14, s0, 6
	s_mov_b32 s15, 0x15800
	v_add_u32_e32 v91, v3, v6
	s_mov_b32 s12, s26
	v_readlane_b32 s37, v251, 17
	v_readlane_b32 s38, v251, 18
	v_readlane_b32 s39, v251, 19
	v_readlane_b32 s40, v251, 20
	v_readlane_b32 s41, v251, 21
	v_readlane_b32 s42, v251, 22
	v_readlane_b32 s43, v251, 23
	v_readlane_b32 s46, v251, 26
	v_readlane_b32 s47, v251, 27
	v_readlane_b32 s48, v251, 28
	v_readlane_b32 s49, v251, 29
	v_readlane_b32 s50, v251, 30
	v_readlane_b32 s51, v251, 31
	s_branch .LBB0_20

.LBB0_680:
	s_lshr_b32 s11, s54, 6
	s_cmpk_lt_i32 s95, 0x700
	s_cselect_b64 s[0:1], -1, 0
	v_writelane_b32 v252, s0, 9
	s_ashr_i32 s81, s95, 31
	s_ashr_i32 s14, s97, 31
	v_writelane_b32 v252, s1, 10
	s_lshr_b32 s0, s81, 29
	s_add_i32 s12, s95, s0
	s_and_b32 s1, s12, -8
	s_ashr_i32 s0, s12, 3
	s_sub_i32 s1, s95, s1
	v_readlane_b32 s16, v251, 2
	v_readlane_b32 s17, v251, 3
	s_add_u32 s2, s16, 0x4200
	s_addc_u32 s3, s17, 0
	v_writelane_b32 v251, s2, 63
	s_lshl_b32 s87, s55, 8
	v_readlane_b32 s36, v251, 16
	v_writelane_b32 v252, s3, 0
	s_add_u32 s2, s56, s87
	s_addc_u32 s3, s57, 0
	s_add_u32 s4, s2, 0x1400
	s_addc_u32 s5, s3, 0
	v_writelane_b32 v252, s4, 11
	s_add_u32 s2, s2, 0x2400
	s_addc_u32 s3, s3, 0
	v_writelane_b32 v252, s5, 12
	v_writelane_b32 v252, s2, 13
	v_readlane_b32 s44, v251, 24
	v_readlane_b32 s45, v251, 25
	v_writelane_b32 v252, s3, 14
	s_add_u32 s2, s16, 0x7400
	s_addc_u32 s3, s17, 0
	v_writelane_b32 v252, s2, 15
	s_mov_b32 s77, 0
	v_readlane_b32 s42, v251, 22
	v_writelane_b32 v252, s3, 16
	s_add_u32 s2, s16, 0x7500
	s_addc_u32 s3, s17, 0
	v_writelane_b32 v252, s2, 17
	s_cmp_lt_i32 s95, 64
	v_readlane_b32 s43, v251, 23
	v_writelane_b32 v252, s3, 18
	s_cselect_b64 s[2:3], -1, 0
	s_lshl_b32 s9, s1, 3
	v_writelane_b32 v252, s2, 19
	s_cmp_gt_i32 s95, 63
	v_readlane_b32 s50, v251, 30
	v_writelane_b32 v252, s3, 20
	s_cselect_b64 s[2:3], -1, 0
	v_writelane_b32 v252, s2, 21
	v_readlane_b32 s51, v251, 31
	v_readlane_b32 s18, v251, 50
	v_writelane_b32 v252, s3, 22
	s_sub_i32 s2, s95, 64
	s_cmp_lt_u32 s2, 64
	v_writelane_b32 v252, s2, 23
	s_cselect_b64 s[2:3], -1, 0
	s_lshl_b32 s19, s95, 3
	s_and_b32 s7, s19, 56
	s_bfe_u32 s8, s95, 0x30003
	v_writelane_b32 v252, s2, 24
	s_cmpk_eq_i32 s97, 0x100
	v_readlane_b32 s37, v251, 17
	v_writelane_b32 v252, s3, 25
	s_cselect_b64 s[2:3], -1, 0
	s_and_b64 s[4:5], s[2:3], exec
	s_cselect_b32 s6, 0x80, 0
	s_sub_i32 s4, s97, s6
	s_cmp_ge_i32 s95, s6
	s_cselect_b64 s[20:21], -1, 0
	v_writelane_b32 v252, s20, 26
	s_mul_i32 s5, s11, 0x2100
	s_add_i32 s5, s5, 0
	v_writelane_b32 v252, s21, 27
	v_writelane_b32 v252, s5, 28
	s_sub_i32 s5, s95, s6
	s_lshl_b32 s5, s5, 3
	s_add_i32 s28, s5, s11
	s_cmpk_lt_i32 s28, 0x4800
	s_cselect_b64 s[20:21], -1, 0
	v_writelane_b32 v252, s20, 29
	v_readlane_b32 s38, v251, 18
	v_readlane_b32 s39, v251, 19
	v_writelane_b32 v252, s21, 30
	v_readlane_b32 s20, v251, 8
	v_readlane_b32 s22, v251, 10
	v_readlane_b32 s23, v251, 11
	s_add_u32 s22, s22, 0x15800000
	s_addc_u32 s23, s23, 0
	s_add_u32 s70, s44, 0x8000
	v_writelane_b32 v252, s22, 5
	s_addc_u32 s71, s45, 0
	s_lshl_b32 s4, s4, 3
	v_writelane_b32 v252, s23, 6
	s_cmp_lt_i32 s95, 32
	v_writelane_b32 v252, s4, 31
	s_cselect_b64 s[4:5], -1, 0
	v_writelane_b32 v252, s4, 32
	s_lshl_b32 s10, s1, 2
	v_readlane_b32 s21, v251, 9
	v_writelane_b32 v252, s5, 33
	s_add_u32 s4, s16, 0x1000
	s_addc_u32 s5, s17, 0
	v_writelane_b32 v252, s4, 34
	s_cmpk_lt_i32 s95, 0x800
	v_readlane_b32 s24, v251, 12
	v_writelane_b32 v252, s5, 35
	s_cselect_b64 s[4:5], -1, 0
	v_writelane_b32 v252, s4, 36
	s_and_b32 s13, s1, 3
	s_add_i32 s76, s1, 32
	v_writelane_b32 v252, s5, 37
	s_lshl_b32 s5, s12, 2
	s_and_b32 s12, s5, 0xffffffe0
	s_ashr_i32 s4, s1, 2
	s_sub_i32 s15, 0x1fe0, s12
	s_ashr_i32 s5, s4, 31
	v_writelane_b32 v252, s15, 38
	s_ashr_i32 s15, s15, 31
	v_writelane_b32 v252, s15, 39
	s_lshl_b64 s[4:5], s[4:5], 26
	v_writelane_b32 v252, s4, 40
	s_add_i32 s22, s11, s19
	v_readlane_b32 s25, v251, 13
	v_writelane_b32 v252, s5, 41
	s_lshl_b32 s4, s13, 10
	v_writelane_b32 v252, s4, 42
	s_lshl_b64 s[4:5], s[76:77], 21
	v_writelane_b32 v252, s4, 43
	v_readlane_b32 s26, v251, 14
	v_readlane_b32 s27, v251, 15
	v_writelane_b32 v252, s5, 44
	s_sub_i32 s4, 0x1de1, s12
	s_max_i32 s4, s4, 0
	s_and_b32 s76, s4, 0x7fffffc0
	s_lshl_b64 s[4:5], s[76:77], 8
	v_writelane_b32 v252, s4, 45
	v_readlane_b32 s40, v251, 20
	v_readlane_b32 s41, v251, 21
	v_writelane_b32 v252, s5, 46
	s_add_u32 s4, s20, 0x800000
	s_addc_u32 s5, s21, 0
	v_writelane_b32 v252, s4, 47
	v_readlane_b32 s46, v251, 26
	v_readlane_b32 s47, v251, 27
	v_writelane_b32 v252, s5, 48
	s_mov_b64 s[4:5], s[52:53]
	v_readlane_b32 s52, v251, 32
	v_readlane_b32 s64, v251, 44
	v_readlane_b32 s65, v251, 45
	s_mov_b64 s[24:25], s[64:65]
	s_mov_b64 s[64:65], s[4:5]
	s_add_u32 s4, s24, 0x800000
	s_addc_u32 s5, s25, 0
	v_writelane_b32 v252, s4, 49
	v_readlane_b32 s67, v251, 47
	s_mov_b32 s67, s14
	v_writelane_b32 v252, s5, 50
	s_add_u32 s4, s42, 0x8000
	s_addc_u32 s5, s43, 0
	s_lshl_b32 s90, s97, 3
	v_writelane_b32 v252, s4, 51
	s_cmpk_lt_i32 s95, 0x400
	v_readlane_b32 s56, v251, 36
	v_writelane_b32 v252, s5, 52
	s_cselect_b64 s[4:5], -1, 0
	v_writelane_b32 v252, s4, 53
	v_readlane_b32 s57, v251, 37
	v_readlane_b32 s58, v251, 38
	v_writelane_b32 v252, s5, 54
	s_ashr_i32 s4, s95, 4
	s_lshl_b32 s5, s95, 1
	s_and_b32 s4, s4, -16
	s_and_b32 s5, s5, 12
	s_or_b32 s4, s4, s5
	s_bfe_u32 s5, s95, 0x20006
	s_or_b32 s20, s4, s5
	s_and_b32 s4, s19, 8
	s_or_b32 s23, s4, s8
	s_mov_b64 s[4:5], 0
	v_writelane_b32 v252, s4, 55
	s_cmp_lg_u64 s[50:51], 0
	v_readlane_b32 s59, v251, 39
	v_writelane_b32 v252, s5, 56
	s_cselect_b64 s[4:5], -1, 0
	v_writelane_b32 v252, s4, 57
	s_cmp_gt_i32 s65, 3
	v_readlane_b32 s48, v251, 28
	v_writelane_b32 v252, s5, 58
	s_cselect_b64 s[4:5], -1, 0
	v_writelane_b32 v252, s4, 59
	s_cmpk_gt_i32 s97, 0xff
	v_readlane_b32 s49, v251, 29
	v_writelane_b32 v252, s5, 60
	s_cselect_b64 s[4:5], -1, 0
	v_writelane_b32 v252, s4, 61
	s_cmpk_lt_i32 s95, 0x80
	v_readlane_b32 s53, v251, 33
	v_writelane_b32 v252, s5, 62
	s_cselect_b64 s[4:5], -1, 0
	s_lshl_b32 s14, s1, 4
	v_writelane_b32 v252, s4, 63
	s_cmpk_lt_u32 s95, 0x100
	v_readlane_b32 s54, v251, 34
	v_writelane_b32 v253, s5, 0
	s_cselect_b64 s[4:5], -1, 0
	v_writelane_b32 v253, s4, 1
	s_lshr_b32 s11, s95, 5
	s_or_b32 s12, s7, s11
	v_writelane_b32 v253, s5, 2
	s_bfe_u32 s4, s95, 0x10003
	s_lshl_b32 s13, s12, 21
	s_lshl_b32 s25, s4, 20
	s_lshl_b32 s12, s12, 8
	s_lshl_b32 s4, s4, 7
	s_bfe_u32 s5, s95, 0x10004
	v_writelane_b32 v253, s13, 3
	s_or_b32 s4, s12, s4
	s_lshl_b32 s24, s5, 21
	v_writelane_b32 v253, s4, 4
	s_lshl_b32 s4, s5, 8
	s_cmpk_gt_i32 s95, 0x7f
	v_writelane_b32 v253, s4, 5
	s_cselect_b64 s[4:5], -1, 0
	v_writelane_b32 v253, s4, 6
	v_readlane_b32 s55, v251, 35
	v_readlane_b32 s60, v251, 40
	v_writelane_b32 v253, s5, 7
	s_add_i32 s5, s95, 0xffffff80
	s_cmp_lt_u32 s5, 16
	s_cselect_b64 s[12:13], -1, 0
	s_add_i32 s4, s95, 0x78
	v_writelane_b32 v253, s12, 8
	s_cmp_lt_u32 s5, 8
	v_readlane_b32 s61, v251, 41
	v_writelane_b32 v253, s13, 9
	s_cselect_b32 s12, s95, s4
	s_cmp_gt_u32 s5, 7
	v_writelane_b32 v253, s5, 10
	s_cselect_b64 s[4:5], -1, 0
	s_and_b32 s15, s12, 0x7f
	s_and_b64 s[12:13], s[4:5], exec
	s_cselect_b32 s12, 0x200000, 0
	v_writelane_b32 v253, s12, 11
	v_writelane_b32 v253, s15, 12
	s_lshl_b32 s12, s15, 21
	v_writelane_b32 v253, s12, 13
	s_add_i32 s12, s18, 0xfffec000
	s_cmpk_gt_i32 s95, 0x8f
	v_writelane_b32 v253, s12, 14
	s_cselect_b64 s[12:13], -1, 0
	s_and_b64 s[2:3], s[12:13], s[2:3]
	v_writelane_b32 v253, s2, 15
	v_cndmask_b32_e64 v226, 0, 1, s[4:5]
	s_movk_i32 s4, 0xe1
	v_writelane_b32 v253, s3, 16
	s_add_i32 s2, s22, 0xfffffb80
	s_cmpk_lt_i32 s2, 0x3f00
	s_cselect_b64 s[2:3], -1, 0
	v_writelane_b32 v253, s2, 17
	s_cmp_lg_u64 s[44:45], 0
	s_mul_i32 s12, s1, 17
	v_writelane_b32 v253, s3, 18
	s_cselect_b64 s[2:3], -1, 0
	v_writelane_b32 v253, s2, 19
	s_cmpk_lt_i32 s95, 0x100
	v_readlane_b32 s62, v251, 42
	v_writelane_b32 v253, s3, 20
	s_cselect_b64 s[2:3], -1, 0
	v_writelane_b32 v253, s2, 21
	s_cmpk_lt_i32 s95, 0x1580
	v_readlane_b32 s63, v251, 43
	v_writelane_b32 v253, s3, 22
	s_cselect_b64 s[2:3], -1, 0
	v_writelane_b32 v253, s2, 23
	s_cmpk_lt_i32 s28, 0x2b00
	v_readlane_b32 s66, v251, 46
	v_writelane_b32 v253, s3, 24
	s_cselect_b64 s[2:3], -1, 0
	v_writelane_b32 v253, s2, 25
	s_cmp_lt_i32 s1, 0
	s_cselect_b32 s4, s4, 0xe0
	v_writelane_b32 v253, s3, 26
	v_cmp_eq_u32_e64 s[2:3], 0, v0
	s_mul_i32 s4, s1, s4
	v_mov_b32_e32 v145, 0
	v_writelane_b32 v253, s2, 27
	s_mov_b64 s[88:89], 0x80
	s_movk_i32 s60, 0xf000
	v_writelane_b32 v253, s3, 28
	s_mul_i32 s2, s1, 9
	s_mul_i32 s3, s1, 5
	s_cselect_b32 s5, s2, s9
	s_movk_i32 s2, 0x2b1
	s_cselect_b32 s3, s3, s10
	s_cselect_b32 s9, s12, s14
	s_cselect_b32 s14, s2, 0x2b0
	s_add_i32 s4, s4, s0
	s_mul_hi_i32 s2, s4, 0x92492493
	s_add_i32 s2, s2, s4
	s_lshr_b32 s10, s2, 31
	s_ashr_i32 s2, s2, 7
	s_add_i32 s2, s2, s10
	s_mul_i32 s10, s2, 0xe0
	s_sub_i32 s4, s4, s10
	s_lshl_b32 s12, s2, 3
	s_bfe_u32 s2, s4, 0x3001c
	s_add_i32 s10, s4, s2
	s_sext_i32_i16 s13, s10
	s_and_b32 s10, s10, 0xfff8
	s_sub_i32 s4, s4, s10
	s_sext_i32_i16 s4, s4
	s_add_i32 s26, s12, s4
	s_ashr_i32 s4, s13, 3
	v_writelane_b32 v253, s4, 29
	s_add_i32 s4, s5, s0
	s_ashr_i32 s5, s4, 31
	s_lshr_b32 s5, s5, 27
	s_add_i32 s5, s4, s5
	s_ashr_i32 s10, s5, 5
	s_and_b32 s5, s5, 0xffe0
	s_sub_i32 s5, s4, s5
	s_bfe_i32 s4, s5, 0x80000
	s_lshr_b32 s12, s4, 7
	s_bfe_u32 s4, s12, 0x30005
	s_lshr_b32 s2, s13, 3
	s_add_i32 s13, s5, s4
	s_bfe_i32 s4, s13, 0x80000
	s_and_b32 s13, s13, 0xf8
	s_sub_i32 s13, s5, s13
	s_lshl_b32 s10, s10, 3
	s_sext_i32_i16 s15, s4
	s_sext_i32_i8 s13, s13
	s_add_i32 s30, s10, s13
	s_ashr_i32 s10, s15, 3
	v_writelane_b32 v253, s10, 30
	s_bfe_u32 s10, s12, 0x40004
	s_add_i32 s5, s5, s10
	s_bfe_i32 s5, s5, 0x80000
	s_sext_i32_i16 s5, s5
	s_lshr_b32 s10, s5, 4
	s_bfe_i64 s[12:13], s[10:11], 0x100000
	s_mov_b32 s10, s30
	s_ashr_i32 s31, s30, 31
	v_writelane_b32 v253, s10, 31
	s_lshr_b32 s4, s15, 3
	s_lshl_b64 s[30:31], s[30:31], 20
	v_writelane_b32 v253, s11, 32
	v_writelane_b32 v253, s30, 33
	s_bfe_i64 s[4:5], s[4:5], 0x100000
	s_lshl_b64 s[4:5], s[4:5], 21
	v_writelane_b32 v253, s31, 34
	v_writelane_b32 v253, s4, 35
	s_add_i32 s3, s3, s0
	s_ashr_i32 s21, s20, 31
	v_writelane_b32 v253, s5, 36
	s_lshl_b64 s[4:5], s[12:13], 24
	v_writelane_b32 v253, s4, 37
	s_mul_i32 s1, s1, s14
	s_add_i32 s1, s1, s0
	v_writelane_b32 v253, s5, 38
	s_or_b32 s4, s7, s8
	v_writelane_b32 v253, s4, 39
	s_lshl_b32 s4, s4, 21
	v_writelane_b32 v253, s4, 40
	s_ashr_i32 s4, s3, 31
	s_lshr_b32 s4, s4, 28
	s_add_i32 s4, s3, s4
	s_ashr_i32 s5, s4, 4
	s_and_b32 s4, s4, 0xfff0
	s_sub_i32 s3, s3, s4
	s_bfe_i32 s4, s3, 0x80000
	s_bfe_u32 s4, s4, 0x3000c
	s_add_i32 s7, s3, s4
	s_bfe_i32 s4, s7, 0x80000
	s_and_b32 s7, s7, 0xf8
	s_sub_i32 s3, s3, s7
	s_lshl_b32 s5, s5, 3
	s_sext_i32_i16 s8, s4
	s_sext_i32_i8 s3, s3
	s_add_i32 s12, s5, s3
	s_ashr_i32 s3, s8, 3
	s_lshr_b32 s4, s8, 3
	v_writelane_b32 v253, s3, 41
	s_mov_b32 s8, s12
	s_ashr_i32 s13, s12, 31
	v_writelane_b32 v253, s8, 42
	s_lshl_b64 s[12:13], s[12:13], 18
	s_bfe_i64 s[4:5], s[4:5], 0x100000
	v_writelane_b32 v253, s9, 43
	v_writelane_b32 v253, s12, 44
	s_lshl_b32 s3, s23, 21
	s_ashr_i32 s27, s26, 31
	v_writelane_b32 v253, s13, 45
	s_lshl_b64 s[12:13], s[4:5], 18
	v_writelane_b32 v253, s12, 46
	s_lshl_b64 s[4:5], s[4:5], 22
	v_mov_b32_e32 v227, 1
	v_writelane_b32 v253, s13, 47
	v_writelane_b32 v253, s4, 48
	s_movk_i32 s86, 0x70
	s_movk_i32 s82, 0xfdff
	v_writelane_b32 v253, s5, 49
	s_lshl_b64 s[4:5], s[20:21], 21
	v_writelane_b32 v253, s4, 50
	s_mov_b32 s78, 0x3e0293ee
	s_mov_b32 s83, 0x41380000
	v_writelane_b32 v253, s5, 51
	v_writelane_b32 v253, s3, 52
	s_lshl_b32 s3, s23, 9
	s_and_b32 s3, s3, 0x1800
	v_writelane_b32 v253, s3, 53
	s_lshl_b32 s3, s23, 19
	v_writelane_b32 v253, s3, 54
	s_add_i32 s3, s9, s0
	s_ashr_i32 s4, s3, 31
	s_lshr_b32 s4, s4, 28
	s_add_i32 s4, s3, s4
	s_ashr_i32 s5, s4, 4
	s_and_b32 s4, s4, 0xfff0
	s_sub_i32 s3, s3, s4
	s_bfe_i32 s4, s3, 0x80000
	s_bfe_u32 s4, s4, 0x3000c
	s_add_i32 s7, s3, s4
	s_bfe_i32 s4, s7, 0x80000
	s_and_b32 s7, s7, 0xf8
	s_sub_i32 s3, s3, s7
	s_lshl_b32 s5, s5, 3
	s_sext_i32_i16 s8, s4
	s_sext_i32_i8 s3, s3
	s_add_i32 s12, s5, s3
	s_ashr_i32 s3, s8, 3
	s_lshr_b32 s4, s8, 3
	v_writelane_b32 v253, s3, 55
	s_mov_b32 s8, s12
	s_ashr_i32 s13, s12, 31
	v_writelane_b32 v253, s8, 56
	s_bfe_i64 s[4:5], s[4:5], 0x100000
	s_lshl_b64 s[4:5], s[4:5], 21
	v_writelane_b32 v253, s9, 57
	s_lshl_b64 s[8:9], s[12:13], 21
	v_writelane_b32 v253, s8, 58
	s_lshl_b32 s3, s23, 18
	s_mul_hi_i32 s0, s1, 0x2fa0be83
	v_writelane_b32 v253, s9, 59
	v_writelane_b32 v253, s4, 60
	s_movk_i32 s61, 0xe000
	s_brev_b32 s63, -2
	v_writelane_b32 v253, s5, 61
	s_mov_b32 s4, s20
	v_writelane_b32 v253, s4, 62
	s_brev_b32 s68, 1
	v_mov_b32_e32 v228, 0x358637bd
	v_writelane_b32 v253, s5, 63
	s_lshl_b64 s[4:5], s[20:21], 18
	v_writelane_b32 v254, s4, 0
	s_mov_b32 s38, 0xf800000
	v_mov_b32_e32 v229, 0x260
	v_writelane_b32 v254, s5, 1
	v_writelane_b32 v254, s23, 2
	v_writelane_b32 v254, s3, 3
	s_lshr_b32 s3, s0, 31
	s_ashr_i32 s0, s0, 7
	s_add_i32 s0, s0, s3
	s_lshl_b32 s3, s0, 3
	s_mulk_i32 s0, 0x2b0
	s_sub_i32 s1, s1, s0
	s_bfe_u32 s0, s1, 0x3001c
	s_add_i32 s4, s1, s0
	s_sext_i32_i16 s5, s4
	s_and_b32 s4, s4, 0xfff8
	s_sub_i32 s1, s1, s4
	s_sext_i32_i16 s1, s1
	s_add_i32 s8, s3, s1
	s_ashr_i32 s1, s5, 3
	v_writelane_b32 v254, s1, 4
	s_mov_b32 s4, s26
	s_lshr_b32 s0, s5, 3
	v_writelane_b32 v254, s4, 5
	s_bfe_i64 s[2:3], s[2:3], 0x100000
	s_lshl_b64 s[2:3], s[2:3], 21
	v_writelane_b32 v254, s5, 6
	s_lshl_b64 s[4:5], s[26:27], 21
	v_writelane_b32 v254, s4, 7
	s_ashr_i32 s9, s8, 31
	s_bfe_i64 s[0:1], s[0:1], 0x100000
	v_writelane_b32 v254, s5, 8
	v_writelane_b32 v254, s2, 9
	s_lshl_b64 s[0:1], s[0:1], 21
	s_mov_b64 s[4:5], -1
	v_writelane_b32 v254, s3, 10
	s_mov_b32 s2, s8
	v_writelane_b32 v254, s2, 11
	s_mov_b32 s39, 0xf7fff000
	s_brev_b32 s40, 31
	v_writelane_b32 v254, s3, 12
	s_lshl_b64 s[2:3], s[8:9], 21
	v_writelane_b32 v254, s2, 13
	s_add_u32 s74, s16, 0x4400
	s_addc_u32 s75, s17, 0
	v_writelane_b32 v254, s3, 14
	v_writelane_b32 v254, s0, 15
	s_ashr_i32 s91, s90, 31
	s_lshl_b64 s[56:57], s[90:91], 13
	v_writelane_b32 v254, s1, 16
	v_writelane_b32 v254, s28, 17
	s_lshl_b32 s0, s28, 6
	v_writelane_b32 v254, s0, 18
	s_lshl_b32 s1, s97, 9
	s_lshl_b32 s0, s6, 9
	s_sub_i32 s0, s1, s0
	v_writelane_b32 v254, s0, 19
	v_writelane_b32 v254, s19, 20
	s_ashr_i32 s0, s19, 31
	v_writelane_b32 v252, s1, 3
	v_writelane_b32 v254, s0, 21
	s_lshl_b64 s[0:1], s[90:91], 2
	v_writelane_b32 v252, s0, 1
	s_lshl_b64 s[58:59], s[90:91], 8
	s_movk_i32 s41, 0xd000
	v_writelane_b32 v252, s1, 2
	s_add_u32 s0, s36, 0x3810
	v_writelane_b32 v254, s0, 22
	s_addc_u32 s0, s37, 0
	v_writelane_b32 v254, s0, 23
	s_lshl_b64 s[0:1], s[90:91], 14
	v_writelane_b32 v254, s0, 24
	v_writelane_b32 v252, s56, 7
	v_mov_b32_e32 v230, 0xff800000
	v_writelane_b32 v254, s1, 25
	v_writelane_b32 v254, s24, 26
	s_or_b32 s0, s24, 0x7000100
	v_writelane_b32 v254, s0, 27
	s_and_b32 s0, s95, 7
	s_lshl_b32 s0, s0, 24
	s_lshl_b32 s1, s11, 21
	s_add_i32 s0, s0, s1
	v_writelane_b32 v254, s25, 28
	s_or_b32 s0, s25, s0
	v_writelane_b32 v254, s0, 29
	s_add_u32 s0, s0, 0x29000080
	v_writelane_b32 v254, s0, 30
	s_addc_u32 s0, 0, 0
	v_writelane_b32 v254, s0, 31
	v_writelane_b32 v254, s22, 32
	s_add_i32 s0, s22, 0xfffff800
	v_writelane_b32 v254, s0, 33
	s_add_i32 s0, s18, 0xfffee000
	v_writelane_b32 v254, s0, 34
	v_readlane_b32 s0, v251, 4
	v_readlane_b32 s2, v251, 6
	v_readlane_b32 s1, v251, 5
	v_readlane_b32 s3, v251, 7
	s_add_u32 s0, s2, 0x3810
	v_writelane_b32 v251, s81, 57
	v_writelane_b32 v254, s0, 35
	s_addc_u32 s0, s3, 0
	v_writelane_b32 v251, s67, 56
	v_writelane_b32 v254, s0, 36
	s_add_i32 s2, 0, 0x18400
	v_writelane_b32 v251, s58, 61
	s_movk_i32 s0, 0x5600
	s_mov_b32 s1, 0x15800
	v_writelane_b32 v254, s2, 37
	v_mov_b32_e32 v231, 0x49742401
	v_mov_b64_e32 v[184:185], 0x400
	v_mov_b64_e32 v[186:187], 0x3ff
	v_mov_b64_e32 v[192:193], 0x1580
	v_mov_b64_e32 v[194:195], 0x157f
	s_mov_b32 s44, s77
	v_writelane_b32 v252, s57, 8
	v_writelane_b32 v251, s59, 62
	s_branch .LBB0_684

.LBB0_869:
	v_readlane_b32 s8, v251, 48
	v_readlane_b32 s9, v251, 54
	v_readlane_b32 s2, v251, 10
	v_readlane_b32 s3, v251, 11
	v_readlane_b32 s4, v251, 24
	v_readlane_b32 s5, v251, 25
	v_readlane_b32 s6, v251, 2
	v_readlane_b32 s7, v251, 3
	s_nop 0
	s_sub_i32 s8, s8, 128
	s_lshl_b32 s8, s8, 3
	s_lshr_b32 s9, s9, 6
	s_add_i32 s8, s8, s9
	s_mul_i32 s32, s9, 0x2100
	s_add_u32 s2, s2, 0x15800000
	s_addc_u32 s3, s3, 0
	s_add_u32 s4, s4, 0x8000
	s_addc_u32 s5, s5, 0
	s_add_u32 s6, s6, 0x13800000
	s_addc_u32 s7, s7, 0
	v_mbcnt_lo_u32_b32 v32, -1, 0
	v_mbcnt_hi_u32_b32 v32, -1, v32
	v_lshrrev_b32_e32 v34, 4, v32
	v_and_b32_e32 v35, 15, v32
	v_and_b32_e32 v36, 7, v32
	v_lshrrev_b32_e32 v37, 3, v32
	v_lshlrev_b32_e32 v30, 3, v34
	v_mul_u32_u24_e32 v38, 0x2b000, v34
	v_lshl_add_u32 v38, v35, 4, v38
	v_mov_b32_e32 v0, v38
	v_add_u32_e32 v1, 0x15800, v38
	v_add_u32_e32 v2, 0xac000, v38
	v_add_u32_e32 v3, 0xc1800, v38
	v_add_u32_e32 v4, 0x158000, v38
	v_add_u32_e32 v5, 0x16d800, v38
	v_add_u32_e32 v6, 0x204000, v38
	v_add_u32_e32 v7, 0x219800, v38
	v_add_u32_e32 v8, 0x2b0000, v38
	v_add_u32_e32 v9, 0x2c5800, v38
	v_add_u32_e32 v10, 0x35c000, v38
	v_add_u32_e32 v11, 0x371800, v38
	v_add_u32_e32 v16, 0x408000, v38
	v_add_u32_e32 v17, 0x41d800, v38
	v_add_u32_e32 v18, 0x4b4000, v38
	v_add_u32_e32 v19, 0x4c9800, v38
	v_lshlrev_b32_e32 v39, 13, v37
	v_lshl_add_u32 v39, v36, 4, v39
	v_mov_b32_e32 v20, v39
	v_add_u32_e32 v21, 0x10000, v39
	v_add_u32_e32 v22, 0x20000, v39
	v_add_u32_e32 v23, 0x30000, v39
	v_add_u32_e32 v24, 0x40000, v39
	v_add_u32_e32 v25, 0x50000, v39
	v_add_u32_e32 v26, 0x60000, v39
	v_add_u32_e32 v27, 0x70000, v39
	v_mul_u32_u24_e32 v28, 0x104, v34
	v_lshl_add_u32 v28, v35, 4, v28
	v_add_u32_e32 v28, s32, v28
	v_mul_u32_u24_e32 v29, 0x410, v36
	v_lshl_add_u32 v29, v37, 2, v29
	v_add_u32_e32 v29, s32, v29
	s_cmpk_lt_i32 s8, 0x4800
	s_cbranch_scc0 .Ltrl_done
	s_mul_hi_u32 s23, s8, 0x2fa0be83
	s_lshr_b32 s23, s23, 6
	s_mul_i32 s25, s23, 0x158
	s_sub_i32 s24, s8, s25
	s_mul_i32 s25, s23, 0x560000
	s_lshl_b32 s33, s24, 8
	s_add_i32 s25, s25, s33
	s_add_u32 s26, s2, s25
	s_addc_u32 s27, s3, 0
	s_lshl_b32 s25, s23, 8
	s_add_u32 s28, s4, s25
	s_addc_u32 s29, s5, 0
	global_load_dwordx4 v[44:47], v0, s[26:27]
	global_load_dwordx4 v[48:51], v1, s[26:27]
	global_load_dwordx4 v[52:55], v2, s[26:27]
	global_load_dwordx4 v[56:59], v3, s[26:27]
	global_load_dwordx4 v[60:63], v4, s[26:27]
	global_load_dwordx4 v[64:67], v5, s[26:27]
	global_load_dwordx4 v[68:71], v6, s[26:27]
	global_load_dwordx4 v[72:75], v7, s[26:27]
	global_load_dwordx4 v[76:79], v8, s[26:27]
	global_load_dwordx4 v[80:83], v9, s[26:27]
	global_load_dwordx4 v[84:87], v10, s[26:27]
	global_load_dwordx4 v[88:91], v11, s[26:27]
	global_load_dwordx4 v[92:95], v16, s[26:27]
	global_load_dwordx4 v[104:107], v17, s[26:27]
	global_load_dwordx4 v[108:111], v18, s[26:27]
	global_load_dwordx4 v[112:115], v19, s[26:27]
	global_load_dwordx2 v[116:117], v30, s[28:29]
	global_load_dwordx2 v[118:119], v30, s[28:29] offset:32
	global_load_dwordx2 v[120:121], v30, s[28:29] offset:64
	global_load_dwordx2 v[122:123], v30, s[28:29] offset:96
	global_load_dwordx2 v[124:125], v30, s[28:29] offset:128
	global_load_dwordx2 v[126:127], v30, s[28:29] offset:160
	global_load_dwordx2 v[128:129], v30, s[28:29] offset:192
	global_load_dwordx2 v[130:131], v30, s[28:29] offset:224
	s_waitcnt vmcnt(0)
	s_branch .Ltrl_body

.Ltrl_body:
	s_mul_hi_u32 s23, s8, 0x2fa0be83
	s_lshr_b32 s23, s23, 6
	s_mul_i32 s25, s23, 0x158
	s_sub_i32 s24, s8, s25
	s_cmpk_ge_u32 s24, 0xac
	s_cselect_b32 s25, 0xac, 0
	s_cselect_b32 s33, 0x80, 0
	s_sub_i32 s24, s24, s25
	s_and_b32 s25, s24, 1
	s_lshl_b32 s25, s25, 6
	s_lshr_b32 s24, s24, 1
	s_lshl_b32 s24, s24, 8
	s_add_i32 s24, s24, s25
	s_add_i32 s24, s24, s33
	s_lshl_b32 s24, s24, 13
	s_lshl_b32 s25, s23, 7
	s_add_i32 s24, s24, s25
	s_add_u32 s30, s6, s24
	s_addc_u32 s31, s7, 0
	v_mul_f32_e32 v34, v44, v116
	v_mul_f32_e32 v35, v48, v117
	v_cvt_pk_bf16_f32 v38, v34, v35
	ds_write_b32 v28, v38
	v_mul_f32_e32 v36, v45, v116
	v_mul_f32_e32 v37, v49, v117
	v_cvt_pk_bf16_f32 v39, v36, v37
	ds_write_b32 v28, v39 offset:4
	v_mul_f32_e32 v34, v46, v116
	v_mul_f32_e32 v35, v50, v117
	v_cvt_pk_bf16_f32 v40, v34, v35
	ds_write_b32 v28, v40 offset:8
	v_mul_f32_e32 v36, v47, v116
	v_mul_f32_e32 v37, v51, v117
	v_cvt_pk_bf16_f32 v41, v36, v37
	ds_write_b32 v28, v41 offset:12
	v_mul_f32_e32 v34, v52, v118
	v_mul_f32_e32 v35, v56, v119
	v_cvt_pk_bf16_f32 v38, v34, v35
	ds_write_b32 v28, v38 offset:1040
	v_mul_f32_e32 v36, v53, v118
	v_mul_f32_e32 v37, v57, v119
	v_cvt_pk_bf16_f32 v39, v36, v37
	ds_write_b32 v28, v39 offset:1044
	v_mul_f32_e32 v34, v54, v118
	v_mul_f32_e32 v35, v58, v119
	v_cvt_pk_bf16_f32 v40, v34, v35
	ds_write_b32 v28, v40 offset:1048
	v_mul_f32_e32 v36, v55, v118
	v_mul_f32_e32 v37, v59, v119
	v_cvt_pk_bf16_f32 v41, v36, v37
	ds_write_b32 v28, v41 offset:1052
	v_mul_f32_e32 v34, v60, v120
	v_mul_f32_e32 v35, v64, v121
	v_cvt_pk_bf16_f32 v38, v34, v35
	ds_write_b32 v28, v38 offset:2080
	v_mul_f32_e32 v36, v61, v120
	v_mul_f32_e32 v37, v65, v121
	v_cvt_pk_bf16_f32 v39, v36, v37
	ds_write_b32 v28, v39 offset:2084
	v_mul_f32_e32 v34, v62, v120
	v_mul_f32_e32 v35, v66, v121
	v_cvt_pk_bf16_f32 v40, v34, v35
	ds_write_b32 v28, v40 offset:2088
	v_mul_f32_e32 v36, v63, v120
	v_mul_f32_e32 v37, v67, v121
	v_cvt_pk_bf16_f32 v41, v36, v37
	ds_write_b32 v28, v41 offset:2092
	v_mul_f32_e32 v34, v68, v122
	v_mul_f32_e32 v35, v72, v123
	v_cvt_pk_bf16_f32 v38, v34, v35
	ds_write_b32 v28, v38 offset:3120
	v_mul_f32_e32 v36, v69, v122
	v_mul_f32_e32 v37, v73, v123
	v_cvt_pk_bf16_f32 v39, v36, v37
	ds_write_b32 v28, v39 offset:3124
	v_mul_f32_e32 v34, v70, v122
	v_mul_f32_e32 v35, v74, v123
	v_cvt_pk_bf16_f32 v40, v34, v35
	ds_write_b32 v28, v40 offset:3128
	v_mul_f32_e32 v36, v71, v122
	v_mul_f32_e32 v37, v75, v123
	v_cvt_pk_bf16_f32 v41, v36, v37
	ds_write_b32 v28, v41 offset:3132
	v_mul_f32_e32 v34, v76, v124
	v_mul_f32_e32 v35, v80, v125
	v_cvt_pk_bf16_f32 v38, v34, v35
	ds_write_b32 v28, v38 offset:4160
	v_mul_f32_e32 v36, v77, v124
	v_mul_f32_e32 v37, v81, v125
	v_cvt_pk_bf16_f32 v39, v36, v37
	ds_write_b32 v28, v39 offset:4164
	v_mul_f32_e32 v34, v78, v124
	v_mul_f32_e32 v35, v82, v125
	v_cvt_pk_bf16_f32 v40, v34, v35
	ds_write_b32 v28, v40 offset:4168
	v_mul_f32_e32 v36, v79, v124
	v_mul_f32_e32 v37, v83, v125
	v_cvt_pk_bf16_f32 v41, v36, v37
	ds_write_b32 v28, v41 offset:4172
	v_mul_f32_e32 v34, v84, v126
	v_mul_f32_e32 v35, v88, v127
	v_cvt_pk_bf16_f32 v38, v34, v35
	ds_write_b32 v28, v38 offset:5200
	v_mul_f32_e32 v36, v85, v126
	v_mul_f32_e32 v37, v89, v127
	v_cvt_pk_bf16_f32 v39, v36, v37
	ds_write_b32 v28, v39 offset:5204
	v_mul_f32_e32 v34, v86, v126
	v_mul_f32_e32 v35, v90, v127
	v_cvt_pk_bf16_f32 v40, v34, v35
	ds_write_b32 v28, v40 offset:5208
	v_mul_f32_e32 v36, v87, v126
	v_mul_f32_e32 v37, v91, v127
	v_cvt_pk_bf16_f32 v41, v36, v37
	ds_write_b32 v28, v41 offset:5212
	v_mul_f32_e32 v34, v92, v128
	v_mul_f32_e32 v35, v104, v129
	v_cvt_pk_bf16_f32 v38, v34, v35
	ds_write_b32 v28, v38 offset:6240
	v_mul_f32_e32 v36, v93, v128
	v_mul_f32_e32 v37, v105, v129
	v_cvt_pk_bf16_f32 v39, v36, v37
	ds_write_b32 v28, v39 offset:6244
	v_mul_f32_e32 v34, v94, v128
	v_mul_f32_e32 v35, v106, v129
	v_cvt_pk_bf16_f32 v40, v34, v35
	ds_write_b32 v28, v40 offset:6248
	v_mul_f32_e32 v36, v95, v128
	v_mul_f32_e32 v37, v107, v129
	v_cvt_pk_bf16_f32 v41, v36, v37
	ds_write_b32 v28, v41 offset:6252
	v_mul_f32_e32 v34, v108, v130
	v_mul_f32_e32 v35, v112, v131
	v_cvt_pk_bf16_f32 v38, v34, v35
	ds_write_b32 v28, v38 offset:7280
	v_mul_f32_e32 v36, v109, v130
	v_mul_f32_e32 v37, v113, v131
	v_cvt_pk_bf16_f32 v39, v36, v37
	ds_write_b32 v28, v39 offset:7284
	v_mul_f32_e32 v34, v110, v130
	v_mul_f32_e32 v35, v114, v131
	v_cvt_pk_bf16_f32 v40, v34, v35
	ds_write_b32 v28, v40 offset:7288
	v_mul_f32_e32 v36, v111, v130
	v_mul_f32_e32 v37, v115, v131
	v_cvt_pk_bf16_f32 v41, v36, v37
	ds_write_b32 v28, v41 offset:7292
	s_add_i32 s9, s8, 0x400
	s_cmpk_lt_i32 s9, 0x4800
	s_cbranch_scc0 .Ltrl_noload
	s_mul_hi_u32 s23, s9, 0x2fa0be83
	s_lshr_b32 s23, s23, 6
	s_mul_i32 s25, s23, 0x158
	s_sub_i32 s24, s9, s25
	s_mul_i32 s25, s23, 0x560000
	s_lshl_b32 s33, s24, 8
	s_add_i32 s25, s25, s33
	s_add_u32 s26, s2, s25
	s_addc_u32 s27, s3, 0
	s_lshl_b32 s25, s23, 8
	s_add_u32 s28, s4, s25
	s_addc_u32 s29, s5, 0
	global_load_dwordx4 v[44:47], v0, s[26:27]
	global_load_dwordx4 v[48:51], v1, s[26:27]
	global_load_dwordx4 v[52:55], v2, s[26:27]
	global_load_dwordx4 v[56:59], v3, s[26:27]
	global_load_dwordx4 v[60:63], v4, s[26:27]
	global_load_dwordx4 v[64:67], v5, s[26:27]
	global_load_dwordx4 v[68:71], v6, s[26:27]
	global_load_dwordx4 v[72:75], v7, s[26:27]
	global_load_dwordx4 v[76:79], v8, s[26:27]
	global_load_dwordx4 v[80:83], v9, s[26:27]
	global_load_dwordx4 v[84:87], v10, s[26:27]
	global_load_dwordx4 v[88:91], v11, s[26:27]
	global_load_dwordx4 v[92:95], v16, s[26:27]
	global_load_dwordx4 v[104:107], v17, s[26:27]
	global_load_dwordx4 v[108:111], v18, s[26:27]
	global_load_dwordx4 v[112:115], v19, s[26:27]
	global_load_dwordx2 v[116:117], v30, s[28:29]
	global_load_dwordx2 v[118:119], v30, s[28:29] offset:32
	global_load_dwordx2 v[120:121], v30, s[28:29] offset:64
	global_load_dwordx2 v[122:123], v30, s[28:29] offset:96
	global_load_dwordx2 v[124:125], v30, s[28:29] offset:128
	global_load_dwordx2 v[126:127], v30, s[28:29] offset:160
	global_load_dwordx2 v[128:129], v30, s[28:29] offset:192
	global_load_dwordx2 v[130:131], v30, s[28:29] offset:224
.Ltrl_noload:
	s_waitcnt lgkmcnt(0)
	ds_read2_b32 v[180:181], v29 offset0:0 offset1:65
	ds_read2_b32 v[182:183], v29 offset0:130 offset1:195
	ds_read2_b32 v[188:189], v29 offset0:8 offset1:73
	ds_read2_b32 v[190:191], v29 offset0:138 offset1:203
	ds_read2_b32 v[196:197], v29 offset0:16 offset1:81
	ds_read2_b32 v[198:199], v29 offset0:146 offset1:211
	ds_read2_b32 v[200:201], v29 offset0:24 offset1:89
	ds_read2_b32 v[202:203], v29 offset0:154 offset1:219
	ds_read2_b32 v[204:205], v29 offset0:32 offset1:97
	ds_read2_b32 v[206:207], v29 offset0:162 offset1:227
	ds_read2_b32 v[232:233], v29 offset0:40 offset1:105
	ds_read2_b32 v[234:235], v29 offset0:170 offset1:235
	ds_read2_b32 v[236:237], v29 offset0:48 offset1:113
	ds_read2_b32 v[238:239], v29 offset0:178 offset1:243
	ds_read2_b32 v[240:241], v29 offset0:56 offset1:121
	ds_read2_b32 v[242:243], v29 offset0:186 offset1:251
	s_waitcnt lgkmcnt(0)
	global_store_dwordx4 v20, v[180:183], s[30:31]
	global_store_dwordx4 v21, v[188:191], s[30:31]
	global_store_dwordx4 v22, v[196:199], s[30:31]
	global_store_dwordx4 v23, v[200:203], s[30:31]
	global_store_dwordx4 v24, v[204:207], s[30:31]
	global_store_dwordx4 v25, v[232:235], s[30:31]
	global_store_dwordx4 v26, v[236:239], s[30:31]
	global_store_dwordx4 v27, v[240:243], s[30:31]
	s_mov_b32 s8, s9
	s_cmpk_lt_i32 s8, 0x4800
	s_cbranch_scc1 .Ltrl_loop

.LBB0_1043:
	s_and_b64 vcc, exec, s[2:3]
	v_readlane_b32 s79, v254, 32
	s_add_i32 s79, s79, 0x2000
	s_cbranch_vccnz .LBB0_1338
	v_readlane_b32 s2, v254, 49
	v_readlane_b32 s3, v254, 50
	s_add_u32 s26, s2, 0x8b200000
	s_addc_u32 s27, s3, 0
	s_add_u32 s4, s2, 0x8a400000
	s_addc_u32 s5, s3, 0
	v_writelane_b32 v254, s4, 52
	s_mov_b32 s97, 0
	s_nop 0
	v_writelane_b32 v254, s5, 53
	s_add_u32 s4, s2, 0x8b400000
	s_addc_u32 s5, s3, 0
	v_writelane_b32 v254, s4, 54
	s_nop 1
	v_writelane_b32 v254, s5, 55
	s_add_u32 s4, s2, 0x93400000
	v_writelane_b32 v254, s4, 56
	s_addc_u32 s4, s3, 0
	v_writelane_b32 v254, s4, 57
	s_add_u32 s4, s2, 0x8800000
	s_addc_u32 s5, s3, 0
	v_writelane_b32 v254, s4, 58
	s_nop 1
	v_writelane_b32 v254, s5, 59
	s_add_u32 s4, s2, 0x7000000
	s_addc_u32 s5, s3, 0
	v_writelane_b32 v254, s4, 60
	s_nop 1
	v_writelane_b32 v254, s5, 61
	s_add_u32 s4, s2, 0x4300000
	s_addc_u32 s5, s3, 0
	v_writelane_b32 v254, s4, 62
	s_nop 1
	v_writelane_b32 v254, s5, 63
	s_add_u32 s4, s2, 0x13800000
	s_addc_u32 s5, s3, 0
	v_writelane_b32 v250, s4, 0
	s_add_u32 s2, s2, 0x8b206000
	s_addc_u32 s3, s3, 0
	v_writelane_b32 v250, s5, 1
	v_writelane_b32 v250, s2, 2
	v_readlane_b32 s79, v254, 32
	s_add_i32 s79, s79, 0x2000
	s_nop 0
	v_writelane_b32 v250, s3, 3
	v_writelane_b32 v250, s26, 4
	v_writelane_b32 v250, s27, 5

.LBB0_1803:
	v_readlane_b32 s8, v251, 48
	v_readlane_b32 s9, v251, 54
	v_readlane_b32 s2, v251, 10
	v_readlane_b32 s3, v251, 11
	v_readlane_b32 s4, v251, 24
	v_readlane_b32 s5, v251, 25
	v_readlane_b32 s6, v251, 2
	v_readlane_b32 s7, v251, 3
	s_nop 0
	s_sub_i32 s8, s8, 144
	s_lshl_b32 s8, s8, 3
	s_lshr_b32 s9, s9, 6
	s_add_i32 s8, s8, s9
	s_mul_i32 s32, s9, 0x2100
	s_add_u32 s6, s6, 0x8c00000
	s_addc_u32 s7, s7, 0
	v_mbcnt_lo_u32_b32 v32, -1, 0
	v_mbcnt_hi_u32_b32 v32, -1, v32
	v_lshrrev_b32_e32 v34, 4, v32
	v_and_b32_e32 v35, 15, v32
	v_and_b32_e32 v36, 7, v32
	v_lshrrev_b32_e32 v37, 3, v32
	v_lshlrev_b32_e32 v30, 3, v34
	v_mul_u32_u24_e32 v38, 0x2b000, v34
	v_lshl_add_u32 v38, v35, 4, v38
	v_mov_b32_e32 v0, v38
	v_add_u32_e32 v1, 0x15800, v38
	v_add_u32_e32 v2, 0xac000, v38
	v_add_u32_e32 v3, 0xc1800, v38
	v_add_u32_e32 v4, 0x158000, v38
	v_add_u32_e32 v5, 0x16d800, v38
	v_add_u32_e32 v6, 0x204000, v38
	v_add_u32_e32 v7, 0x219800, v38
	v_add_u32_e32 v8, 0x2b0000, v38
	v_add_u32_e32 v9, 0x2c5800, v38
	v_add_u32_e32 v10, 0x35c000, v38
	v_add_u32_e32 v11, 0x371800, v38
	v_add_u32_e32 v16, 0x408000, v38
	v_add_u32_e32 v17, 0x41d800, v38
	v_add_u32_e32 v18, 0x4b4000, v38
	v_add_u32_e32 v19, 0x4c9800, v38
	v_lshlrev_b32_e32 v39, 13, v37
	v_lshl_add_u32 v39, v36, 4, v39
	v_mov_b32_e32 v20, v39
	v_add_u32_e32 v21, 0x10000, v39
	v_add_u32_e32 v22, 0x20000, v39
	v_add_u32_e32 v23, 0x30000, v39
	v_add_u32_e32 v24, 0x40000, v39
	v_add_u32_e32 v25, 0x50000, v39
	v_add_u32_e32 v26, 0x60000, v39
	v_add_u32_e32 v27, 0x70000, v39
	v_mul_u32_u24_e32 v28, 0x104, v34
	v_lshl_add_u32 v28, v35, 4, v28
	v_add_u32_e32 v28, s32, v28
	v_mul_u32_u24_e32 v29, 0x410, v36
	v_lshl_add_u32 v29, v37, 2, v29
	v_add_u32_e32 v29, s32, v29
	s_cmpk_lt_i32 s8, 0x3f00
	s_cbranch_scc0 .Ltrx_done
	s_mul_hi_u32 s23, s8, 0x2fa0be83
	s_lshr_b32 s23, s23, 6
	s_mul_i32 s25, s23, 0x158
	s_sub_i32 s24, s8, s25
	s_mul_i32 s25, s23, 0x560000
	s_lshl_b32 s33, s24, 8
	s_add_i32 s25, s25, s33
	s_add_u32 s26, s2, s25
	s_addc_u32 s27, s3, 0
	s_lshl_b32 s25, s23, 8
	s_add_u32 s28, s4, s25
	s_addc_u32 s29, s5, 0
	global_load_dwordx4 v[44:47], v0, s[26:27]
	global_load_dwordx4 v[48:51], v1, s[26:27]
	global_load_dwordx4 v[52:55], v2, s[26:27]
	global_load_dwordx4 v[56:59], v3, s[26:27]
	global_load_dwordx4 v[60:63], v4, s[26:27]
	global_load_dwordx4 v[64:67], v5, s[26:27]
	global_load_dwordx4 v[68:71], v6, s[26:27]
	global_load_dwordx4 v[72:75], v7, s[26:27]
	global_load_dwordx4 v[76:79], v8, s[26:27]
	global_load_dwordx4 v[80:83], v9, s[26:27]
	global_load_dwordx4 v[84:87], v10, s[26:27]
	global_load_dwordx4 v[88:91], v11, s[26:27]
	global_load_dwordx4 v[92:95], v16, s[26:27]
	global_load_dwordx4 v[104:107], v17, s[26:27]
	global_load_dwordx4 v[108:111], v18, s[26:27]
	global_load_dwordx4 v[112:115], v19, s[26:27]
	global_load_dwordx2 v[116:117], v30, s[28:29]
	global_load_dwordx2 v[118:119], v30, s[28:29] offset:32
	global_load_dwordx2 v[120:121], v30, s[28:29] offset:64
	global_load_dwordx2 v[122:123], v30, s[28:29] offset:96
	global_load_dwordx2 v[124:125], v30, s[28:29] offset:128
	global_load_dwordx2 v[126:127], v30, s[28:29] offset:160
	global_load_dwordx2 v[128:129], v30, s[28:29] offset:192
	global_load_dwordx2 v[130:131], v30, s[28:29] offset:224
	s_waitcnt vmcnt(0)
	s_branch .Ltrx_body

.Ltrx_body:
	s_mul_hi_u32 s23, s8, 0x2fa0be83
	s_lshr_b32 s23, s23, 6
	s_mul_i32 s25, s23, 0x158
	s_sub_i32 s24, s8, s25
	s_cmpk_ge_u32 s24, 0xac
	s_cselect_b32 s25, 0xac, 0
	s_cselect_b32 s33, 0x80, 0
	s_sub_i32 s24, s24, s25
	s_and_b32 s25, s24, 1
	s_lshl_b32 s25, s25, 6
	s_lshr_b32 s24, s24, 1
	s_lshl_b32 s24, s24, 8
	s_add_i32 s24, s24, s25
	s_add_i32 s24, s24, s33
	s_lshl_b32 s24, s24, 13
	s_lshl_b32 s25, s23, 7
	s_add_i32 s24, s24, s25
	s_add_u32 s30, s6, s24
	s_addc_u32 s31, s7, 0
	v_mul_f32_e32 v34, v44, v116
	v_mul_f32_e32 v35, v48, v117
	v_cvt_pk_bf16_f32 v38, v34, v35
	ds_write_b32 v28, v38
	v_mul_f32_e32 v36, v45, v116
	v_mul_f32_e32 v37, v49, v117
	v_cvt_pk_bf16_f32 v39, v36, v37
	ds_write_b32 v28, v39 offset:4
	v_mul_f32_e32 v34, v46, v116
	v_mul_f32_e32 v35, v50, v117
	v_cvt_pk_bf16_f32 v40, v34, v35
	ds_write_b32 v28, v40 offset:8
	v_mul_f32_e32 v36, v47, v116
	v_mul_f32_e32 v37, v51, v117
	v_cvt_pk_bf16_f32 v41, v36, v37
	ds_write_b32 v28, v41 offset:12
	v_mul_f32_e32 v34, v52, v118
	v_mul_f32_e32 v35, v56, v119
	v_cvt_pk_bf16_f32 v38, v34, v35
	ds_write_b32 v28, v38 offset:1040
	v_mul_f32_e32 v36, v53, v118
	v_mul_f32_e32 v37, v57, v119
	v_cvt_pk_bf16_f32 v39, v36, v37
	ds_write_b32 v28, v39 offset:1044
	v_mul_f32_e32 v34, v54, v118
	v_mul_f32_e32 v35, v58, v119
	v_cvt_pk_bf16_f32 v40, v34, v35
	ds_write_b32 v28, v40 offset:1048
	v_mul_f32_e32 v36, v55, v118
	v_mul_f32_e32 v37, v59, v119
	v_cvt_pk_bf16_f32 v41, v36, v37
	ds_write_b32 v28, v41 offset:1052
	v_mul_f32_e32 v34, v60, v120
	v_mul_f32_e32 v35, v64, v121
	v_cvt_pk_bf16_f32 v38, v34, v35
	ds_write_b32 v28, v38 offset:2080
	v_mul_f32_e32 v36, v61, v120
	v_mul_f32_e32 v37, v65, v121
	v_cvt_pk_bf16_f32 v39, v36, v37
	ds_write_b32 v28, v39 offset:2084
	v_mul_f32_e32 v34, v62, v120
	v_mul_f32_e32 v35, v66, v121
	v_cvt_pk_bf16_f32 v40, v34, v35
	ds_write_b32 v28, v40 offset:2088
	v_mul_f32_e32 v36, v63, v120
	v_mul_f32_e32 v37, v67, v121
	v_cvt_pk_bf16_f32 v41, v36, v37
	ds_write_b32 v28, v41 offset:2092
	v_mul_f32_e32 v34, v68, v122
	v_mul_f32_e32 v35, v72, v123
	v_cvt_pk_bf16_f32 v38, v34, v35
	ds_write_b32 v28, v38 offset:3120
	v_mul_f32_e32 v36, v69, v122
	v_mul_f32_e32 v37, v73, v123
	v_cvt_pk_bf16_f32 v39, v36, v37
	ds_write_b32 v28, v39 offset:3124
	v_mul_f32_e32 v34, v70, v122
	v_mul_f32_e32 v35, v74, v123
	v_cvt_pk_bf16_f32 v40, v34, v35
	ds_write_b32 v28, v40 offset:3128
	v_mul_f32_e32 v36, v71, v122
	v_mul_f32_e32 v37, v75, v123
	v_cvt_pk_bf16_f32 v41, v36, v37
	ds_write_b32 v28, v41 offset:3132
	v_mul_f32_e32 v34, v76, v124
	v_mul_f32_e32 v35, v80, v125
	v_cvt_pk_bf16_f32 v38, v34, v35
	ds_write_b32 v28, v38 offset:4160
	v_mul_f32_e32 v36, v77, v124
	v_mul_f32_e32 v37, v81, v125
	v_cvt_pk_bf16_f32 v39, v36, v37
	ds_write_b32 v28, v39 offset:4164
	v_mul_f32_e32 v34, v78, v124
	v_mul_f32_e32 v35, v82, v125
	v_cvt_pk_bf16_f32 v40, v34, v35
	ds_write_b32 v28, v40 offset:4168
	v_mul_f32_e32 v36, v79, v124
	v_mul_f32_e32 v37, v83, v125
	v_cvt_pk_bf16_f32 v41, v36, v37
	ds_write_b32 v28, v41 offset:4172
	v_mul_f32_e32 v34, v84, v126
	v_mul_f32_e32 v35, v88, v127
	v_cvt_pk_bf16_f32 v38, v34, v35
	ds_write_b32 v28, v38 offset:5200
	v_mul_f32_e32 v36, v85, v126
	v_mul_f32_e32 v37, v89, v127
	v_cvt_pk_bf16_f32 v39, v36, v37
	ds_write_b32 v28, v39 offset:5204
	v_mul_f32_e32 v34, v86, v126
	v_mul_f32_e32 v35, v90, v127
	v_cvt_pk_bf16_f32 v40, v34, v35
	ds_write_b32 v28, v40 offset:5208
	v_mul_f32_e32 v36, v87, v126
	v_mul_f32_e32 v37, v91, v127
	v_cvt_pk_bf16_f32 v41, v36, v37
	ds_write_b32 v28, v41 offset:5212
	v_mul_f32_e32 v34, v92, v128
	v_mul_f32_e32 v35, v104, v129
	v_cvt_pk_bf16_f32 v38, v34, v35
	ds_write_b32 v28, v38 offset:6240
	v_mul_f32_e32 v36, v93, v128
	v_mul_f32_e32 v37, v105, v129
	v_cvt_pk_bf16_f32 v39, v36, v37
	ds_write_b32 v28, v39 offset:6244
	v_mul_f32_e32 v34, v94, v128
	v_mul_f32_e32 v35, v106, v129
	v_cvt_pk_bf16_f32 v40, v34, v35
	ds_write_b32 v28, v40 offset:6248
	v_mul_f32_e32 v36, v95, v128
	v_mul_f32_e32 v37, v107, v129
	v_cvt_pk_bf16_f32 v41, v36, v37
	ds_write_b32 v28, v41 offset:6252
	v_mul_f32_e32 v34, v108, v130
	v_mul_f32_e32 v35, v112, v131
	v_cvt_pk_bf16_f32 v38, v34, v35
	ds_write_b32 v28, v38 offset:7280
	v_mul_f32_e32 v36, v109, v130
	v_mul_f32_e32 v37, v113, v131
	v_cvt_pk_bf16_f32 v39, v36, v37
	ds_write_b32 v28, v39 offset:7284
	v_mul_f32_e32 v34, v110, v130
	v_mul_f32_e32 v35, v114, v131
	v_cvt_pk_bf16_f32 v40, v34, v35
	ds_write_b32 v28, v40 offset:7288
	v_mul_f32_e32 v36, v111, v130
	v_mul_f32_e32 v37, v115, v131
	v_cvt_pk_bf16_f32 v41, v36, v37
	ds_write_b32 v28, v41 offset:7292
	s_add_i32 s9, s8, 0x380
	s_cmpk_lt_i32 s9, 0x3f00
	s_cbranch_scc0 .Ltrx_noload
	s_mul_hi_u32 s23, s9, 0x2fa0be83
	s_lshr_b32 s23, s23, 6
	s_mul_i32 s25, s23, 0x158
	s_sub_i32 s24, s9, s25
	s_mul_i32 s25, s23, 0x560000
	s_lshl_b32 s33, s24, 8
	s_add_i32 s25, s25, s33
	s_add_u32 s26, s2, s25
	s_addc_u32 s27, s3, 0
	s_lshl_b32 s25, s23, 8
	s_add_u32 s28, s4, s25
	s_addc_u32 s29, s5, 0
	global_load_dwordx4 v[44:47], v0, s[26:27]
	global_load_dwordx4 v[48:51], v1, s[26:27]
	global_load_dwordx4 v[52:55], v2, s[26:27]
	global_load_dwordx4 v[56:59], v3, s[26:27]
	global_load_dwordx4 v[60:63], v4, s[26:27]
	global_load_dwordx4 v[64:67], v5, s[26:27]
	global_load_dwordx4 v[68:71], v6, s[26:27]
	global_load_dwordx4 v[72:75], v7, s[26:27]
	global_load_dwordx4 v[76:79], v8, s[26:27]
	global_load_dwordx4 v[80:83], v9, s[26:27]
	global_load_dwordx4 v[84:87], v10, s[26:27]
	global_load_dwordx4 v[88:91], v11, s[26:27]
	global_load_dwordx4 v[92:95], v16, s[26:27]
	global_load_dwordx4 v[104:107], v17, s[26:27]
	global_load_dwordx4 v[108:111], v18, s[26:27]
	global_load_dwordx4 v[112:115], v19, s[26:27]
	global_load_dwordx2 v[116:117], v30, s[28:29]
	global_load_dwordx2 v[118:119], v30, s[28:29] offset:32
	global_load_dwordx2 v[120:121], v30, s[28:29] offset:64
	global_load_dwordx2 v[122:123], v30, s[28:29] offset:96
	global_load_dwordx2 v[124:125], v30, s[28:29] offset:128
	global_load_dwordx2 v[126:127], v30, s[28:29] offset:160
	global_load_dwordx2 v[128:129], v30, s[28:29] offset:192
	global_load_dwordx2 v[130:131], v30, s[28:29] offset:224
.Ltrx_noload:
	s_waitcnt lgkmcnt(0)
	ds_read2_b32 v[180:181], v29 offset0:0 offset1:65
	ds_read2_b32 v[182:183], v29 offset0:130 offset1:195
	ds_read2_b32 v[188:189], v29 offset0:8 offset1:73
	ds_read2_b32 v[190:191], v29 offset0:138 offset1:203
	ds_read2_b32 v[196:197], v29 offset0:16 offset1:81
	ds_read2_b32 v[198:199], v29 offset0:146 offset1:211
	ds_read2_b32 v[200:201], v29 offset0:24 offset1:89
	ds_read2_b32 v[202:203], v29 offset0:154 offset1:219
	ds_read2_b32 v[204:205], v29 offset0:32 offset1:97
	ds_read2_b32 v[206:207], v29 offset0:162 offset1:227
	ds_read2_b32 v[232:233], v29 offset0:40 offset1:105
	ds_read2_b32 v[234:235], v29 offset0:170 offset1:235
	ds_read2_b32 v[236:237], v29 offset0:48 offset1:113
	ds_read2_b32 v[238:239], v29 offset0:178 offset1:243
	ds_read2_b32 v[240:241], v29 offset0:56 offset1:121
	ds_read2_b32 v[242:243], v29 offset0:186 offset1:251
	s_waitcnt lgkmcnt(0)
	global_store_dwordx4 v20, v[180:183], s[30:31]
	global_store_dwordx4 v21, v[188:191], s[30:31]
	global_store_dwordx4 v22, v[196:199], s[30:31]
	global_store_dwordx4 v23, v[200:203], s[30:31]
	global_store_dwordx4 v24, v[204:207], s[30:31]
	global_store_dwordx4 v25, v[232:235], s[30:31]
	global_store_dwordx4 v26, v[236:239], s[30:31]
	global_store_dwordx4 v27, v[240:243], s[30:31]
	s_mov_b32 s8, s9
	s_cmpk_lt_i32 s8, 0x3f00
	s_cbranch_scc1 .Ltrx_loop
